# nt_hint_on_final_norm_output_stores
# baseline (speedup 1.0000x reference)
.LBB0_1309:
	s_ashr_i32 s5, s4, 31
	s_add_i32 s0, s4, s86
	s_lshl_b64 s[8:9], s[4:5], 2
	s_add_u32 s8, s6, s8
	s_addc_u32 s9, s7, s9
	s_ashr_i32 s1, s0, 31
	global_load_dword v46, v17, s[8:9]
	s_add_u32 s8, s8, s2
	s_addc_u32 s9, s9, s3
	global_load_dword v47, v17, s[8:9]
	s_lshl_b64 s[10:11], s[4:5], 11
	s_lshl_b64 s[12:13], s[0:1], 11
	v_lshl_add_u64 v[22:23], v[18:19], 0, s[10:11]
	v_lshl_add_u64 v[24:25], v[18:19], 0, s[12:13]
	global_load_dwordx2 v[26:27], v[22:23], off
	global_load_dwordx2 v[28:29], v[24:25], off
	global_load_dwordx2 v[30:31], v[22:23], off offset:512
	global_load_dwordx2 v[32:33], v[24:25], off offset:512
	global_load_dwordx2 v[34:35], v[22:23], off offset:1024
	global_load_dwordx2 v[36:37], v[24:25], off offset:1024
	global_load_dwordx2 v[42:43], v[22:23], off offset:1536
	global_load_dwordx2 v[44:45], v[24:25], off offset:1536
	s_lshl_b64 s[14:15], s[4:5], 12
	s_lshl_b64 s[16:17], s[0:1], 12
	s_add_i32 s4, s0, s86
	v_lshl_add_u64 v[38:39], v[20:21], 0, s[14:15]
	v_lshl_add_u64 v[40:41], v[20:21], 0, s[16:17]
	s_cmp_lt_i32 s4, 0x10000
	s_waitcnt vmcnt(9)
	v_fmamk_f32 v22, v46, 0x3a800000, v16
	v_mul_f32_e32 v23, 0x4b800000, v22
	v_cmp_gt_f32_e32 vcc, s18, v22
	s_waitcnt vmcnt(8)
	v_fmamk_f32 v58, v47, 0x3a800000, v16
	v_mul_f32_e32 v60, 0x4b800000, v58
	v_cndmask_b32_e32 v22, v22, v23, vcc
	v_cmp_gt_f32_e64 s[0:1], s18, v58
	v_rsq_f32_e32 v59, v22
	s_waitcnt vmcnt(7)
	v_lshlrev_b32_e32 v22, 16, v26
	v_cndmask_b32_e64 v58, v58, v60, s[0:1]
	v_rsq_f32_e32 v60, v58
	v_mul_f32_e32 v58, 0x45800000, v59
	v_and_b32_e32 v23, 0xffff0000, v26
	v_lshlrev_b32_e32 v24, 16, v27
	v_and_b32_e32 v25, 0xffff0000, v27
	v_cndmask_b32_e32 v58, v59, v58, vcc
	v_mul_f32_e32 v59, 0x45800000, v60
	s_waitcnt vmcnt(6)
	v_lshlrev_b32_e32 v46, 16, v28
	v_and_b32_e32 v47, 0xffff0000, v28
	v_lshlrev_b32_e32 v48, 16, v29
	v_and_b32_e32 v49, 0xffff0000, v29
	s_waitcnt vmcnt(5)
	v_lshlrev_b32_e32 v26, 16, v30
	v_and_b32_e32 v27, 0xffff0000, v30
	v_lshlrev_b32_e32 v28, 16, v31
	v_and_b32_e32 v29, 0xffff0000, v31
	s_waitcnt vmcnt(4)
	v_lshlrev_b32_e32 v50, 16, v32
	v_and_b32_e32 v51, 0xffff0000, v32
	v_lshlrev_b32_e32 v52, 16, v33
	v_and_b32_e32 v53, 0xffff0000, v33
	s_waitcnt vmcnt(3)
	v_lshlrev_b32_e32 v30, 16, v34
	v_and_b32_e32 v31, 0xffff0000, v34
	v_lshlrev_b32_e32 v32, 16, v35
	v_and_b32_e32 v33, 0xffff0000, v35
	s_waitcnt vmcnt(2)
	v_lshlrev_b32_e32 v54, 16, v36
	v_and_b32_e32 v55, 0xffff0000, v36
	v_lshlrev_b32_e32 v56, 16, v37
	v_and_b32_e32 v57, 0xffff0000, v37
	s_waitcnt vmcnt(1)
	v_lshlrev_b32_e32 v34, 16, v42
	v_and_b32_e32 v35, 0xffff0000, v42
	v_lshlrev_b32_e32 v36, 16, v43
	v_and_b32_e32 v37, 0xffff0000, v43
	v_pk_mul_f32 v[22:23], v[58:59], v[22:23] op_sel_hi:[0,1]
	v_pk_mul_f32 v[24:25], v[58:59], v[24:25] op_sel_hi:[0,1]
	v_pk_mul_f32 v[26:27], v[58:59], v[26:27] op_sel_hi:[0,1]
	v_pk_mul_f32 v[28:29], v[58:59], v[28:29] op_sel_hi:[0,1]
	v_pk_mul_f32 v[30:31], v[58:59], v[30:31] op_sel_hi:[0,1]
	v_pk_mul_f32 v[32:33], v[58:59], v[32:33] op_sel_hi:[0,1]
	v_pk_mul_f32 v[34:35], v[58:59], v[34:35] op_sel_hi:[0,1]
	v_pk_mul_f32 v[36:37], v[58:59], v[36:37] op_sel_hi:[0,1]
	v_cndmask_b32_e64 v58, v60, v59, s[0:1]
	v_pk_mul_f32 v[24:25], v[2:3], v[24:25]
	v_pk_mul_f32 v[22:23], v[0:1], v[22:23]
	s_waitcnt vmcnt(0)
	v_lshlrev_b32_e32 v42, 16, v44
	v_and_b32_e32 v43, 0xffff0000, v44
	v_lshlrev_b32_e32 v44, 16, v45
	v_and_b32_e32 v45, 0xffff0000, v45
	v_pk_mul_f32 v[28:29], v[6:7], v[28:29]
	v_pk_mul_f32 v[26:27], v[4:5], v[26:27]
	v_pk_mul_f32 v[32:33], v[10:11], v[32:33]
	v_pk_mul_f32 v[30:31], v[8:9], v[30:31]
	v_pk_mul_f32 v[36:37], v[14:15], v[36:37]
	v_pk_mul_f32 v[34:35], v[12:13], v[34:35]
	global_store_dwordx4 v[38:39], v[22:25], off nt
	global_store_dwordx4 v[38:39], v[26:29], off offset:1024 nt
	global_store_dwordx4 v[38:39], v[30:33], off offset:2048 nt
	v_pk_mul_f32 v[22:23], v[58:59], v[46:47] op_sel_hi:[0,1]
	v_pk_mul_f32 v[24:25], v[58:59], v[48:49] op_sel_hi:[0,1]
	v_pk_mul_f32 v[26:27], v[58:59], v[50:51] op_sel_hi:[0,1]
	v_pk_mul_f32 v[28:29], v[58:59], v[52:53] op_sel_hi:[0,1]
	v_pk_mul_f32 v[30:31], v[58:59], v[54:55] op_sel_hi:[0,1]
	v_pk_mul_f32 v[32:33], v[58:59], v[56:57] op_sel_hi:[0,1]
	global_store_dwordx4 v[38:39], v[34:37], off offset:3072 nt
	v_pk_mul_f32 v[24:25], v[2:3], v[24:25]
	v_pk_mul_f32 v[22:23], v[0:1], v[22:23]
	v_pk_mul_f32 v[34:35], v[58:59], v[42:43] op_sel_hi:[0,1]
	v_pk_mul_f32 v[36:37], v[58:59], v[44:45] op_sel_hi:[0,1]
	v_pk_mul_f32 v[28:29], v[6:7], v[28:29]
	v_pk_mul_f32 v[26:27], v[4:5], v[26:27]
	v_pk_mul_f32 v[32:33], v[10:11], v[32:33]
	v_pk_mul_f32 v[30:31], v[8:9], v[30:31]
	v_pk_mul_f32 v[36:37], v[14:15], v[36:37]
	v_pk_mul_f32 v[34:35], v[12:13], v[34:35]
	global_store_dwordx4 v[40:41], v[22:25], off nt
	global_store_dwordx4 v[40:41], v[26:29], off offset:1024 nt
	global_store_dwordx4 v[40:41], v[30:33], off offset:2048 nt
	global_store_dwordx4 v[40:41], v[34:37], off offset:3072 nt
	s_cbranch_scc1 .LBB0_1309
